# final LayerNorm phase: the two wave reductions per row use DPP row ops plus permlane16/32 swaps instead of twelve ds_bpermute round trips (on top of the parameter hoist)
# baseline (speedup 1.0000x reference)
; __device__ __forceinline__ void phase_ln(KP p, int l) {
;     ...
;     for (int row = blockIdx.x * 8 + wid; row < SEQ; row += gridDim.x * 8) {
;         float* xr = p->out + (size_t)row * DM + lane * 4;
;         f32x4 v[8]; float sm = 0.f;
; #pragma unroll
;         for (int j = 0; j < 8; ++j) { v[j] = *(const f32x4*)(xr + 256 * j); sm += (v[j][0] + v[j][1]) + (v[j][2] + v[j][3]); }
;         const float mean = wave_sum(sm) * (1.f / DM); float sq = 0.f;
.LBB0_900:
	v_ashrrev_i32_e32 v35, 31, v34
	v_lshlrev_b64 v[2:3], 13, v[34:35]
	v_lshl_add_u64 v[60:61], v[38:39], 0, v[2:3]
	global_load_dwordx4 v[30:33], v[60:61], off
	global_load_dwordx4 v[26:29], v[60:61], off offset:1024
	global_load_dwordx4 v[18:21], v[60:61], off offset:2048
	global_load_dwordx4 v[22:25], v[60:61], off offset:3072
	v_add_co_u32_e32 v62, vcc, s2, v60
	s_mov_b64 s[24:25], -1
	s_nop 0
	v_addc_co_u32_e32 v63, vcc, 0, v61, vcc
	global_load_dwordx4 v[10:13], v[62:63], off
	global_load_dwordx4 v[14:17], v[62:63], off offset:1024
	s_waitcnt vmcnt(0)
	v_mov_b32_e32 v2, v30
	v_mov_b32_e32 v3, v26
	v_mov_b32_e32 v4, v31
	v_mov_b32_e32 v5, v27
	v_pk_add_f32 v[2:3], v[2:3], v[4:5]
	v_mov_b32_e32 v4, v32
	v_mov_b32_e32 v5, v28
	v_mov_b32_e32 v6, v33
	v_mov_b32_e32 v7, v29
	v_pk_add_f32 v[4:5], v[4:5], v[6:7]
	v_mov_b32_e32 v6, v18
	v_pk_add_f32 v[2:3], v[2:3], v[4:5]
	v_mov_b32_e32 v4, v19
	v_mov_b32_e32 v5, v20
	v_mov_b32_e32 v7, v21
	v_pk_add_f32 v[4:5], v[4:5], v[6:7]
	v_add_f32_e32 v0, 0, v2
	v_pk_add_f32 v[4:5], v[4:5], v[4:5] op_sel:[0,1] op_sel_hi:[1,0]
	v_add_f32_e32 v2, v0, v3
	v_add_f32_e32 v6, v22, v23
	v_add_f32_e32 v8, v24, v25
	v_mov_b32_e32 v3, v10
	v_mov_b32_e32 v5, v11
	v_mov_b32_e32 v7, v12
	v_mov_b32_e32 v9, v13
	v_pk_add_f32 v[2:3], v[2:3], v[4:5]
	v_pk_add_f32 v[4:5], v[6:7], v[8:9]
	global_load_dwordx4 v[6:9], v[62:63], off offset:2048
	v_pk_add_f32 v[2:3], v[2:3], v[4:5]
	v_mov_b32_e32 v4, v14
	v_pk_add_f32 v[64:65], v[2:3], v[2:3] op_sel:[0,1] op_sel_hi:[1,0]
	v_mov_b32_e32 v2, v15
	v_mov_b32_e32 v3, v16
	v_mov_b32_e32 v5, v17
	v_pk_add_f32 v[2:3], v[2:3], v[4:5]
	s_nop 0
	v_pk_add_f32 v[66:67], v[2:3], v[2:3] op_sel:[0,1] op_sel_hi:[1,0]
	global_load_dwordx4 v[2:5], v[62:63], off offset:3072
	s_waitcnt vmcnt(1)
	v_add_f32_e32 v68, v6, v7
	v_add_f32_e32 v70, v8, v9
	s_waitcnt vmcnt(0)
; __device__ __forceinline__ void phase_ln(KP p, int l) {
;     ...
;         for (int j = 0; j < 8; ++j) { v[j] = *(const f32x4*)(xr + 256 * j); sm += (v[j][0] + v[j][1]) + (v[j][2] + v[j][3]); }
;         const float mean = wave_sum(sm) * (1.f / DM); float sq = 0.f;
; #pragma unroll
;         for (int j = 0; j < 8; ++j) { v[j] = v[j] - mean; sq += (v[j][0] * v[j][0] + v[j][1] * v[j][1]) + (v[j][2] * v[j][2] + v[j][3] * v[j][3]); }
;         const float rstd = rsqrtf(wave_sum(sq) * (1.f / DM) + LN_EPS);
; #pragma unroll
;         for (int j = 0; j < 8; ++j) { const int c = lane * 4 + 256 * j;
;             const f32x4 y = v[j] * rstd * *(const f32x4*)(lng + c) + *(const f32x4*)(lnb + c);
;             *(f32x4*)(xr + 256 * j) = y;
	v_mov_b32_e32 v65, v2
	v_mov_b32_e32 v67, v3
	v_mov_b32_e32 v69, v4
	v_mov_b32_e32 v71, v5
	v_pk_add_f32 v[62:63], v[64:65], v[66:67]
	v_pk_add_f32 v[64:65], v[68:69], v[70:71]
	s_nop 0
	v_pk_add_f32 v[62:63], v[62:63], v[64:65]
	s_nop 0
	v_add_f32_e32 v0, v62, v63
	s_nop 1
	v_add_f32_dpp v0, v0, v0 quad_perm:[1,0,3,2] row_mask:0xf bank_mask:0xf
	s_nop 1
	v_add_f32_dpp v0, v0, v0 quad_perm:[2,3,0,1] row_mask:0xf bank_mask:0xf
	s_nop 1
	v_add_f32_dpp v0, v0, v0 row_half_mirror row_mask:0xf bank_mask:0xf
	s_nop 1
	v_add_f32_dpp v0, v0, v0 row_mirror row_mask:0xf bank_mask:0xf
	v_mov_b32_e32 v62, v0
	s_nop 1
	v_permlane16_swap_b32_e32 v0, v62
	v_add_f32_e32 v0, v0, v62
	v_mov_b32_e32 v62, v0
	s_nop 1
	v_permlane32_swap_b32_e32 v0, v62
	v_add_f32_e32 v77, v0, v62
	v_fmamk_f32 v31, v77, 0xba000000, v31
	v_fmamk_f32 v27, v77, 0xba000000, v27
	v_fmamk_f32 v79, v77, 0xba000000, v33
	v_fmamk_f32 v78, v77, 0xba000000, v32
	v_fmac_f32_e32 v30, 0xba000000, v77
	v_fmac_f32_e32 v26, 0xba000000, v77
	v_mov_b32_e32 v32, v31
	v_mov_b32_e32 v33, v27
	v_fmamk_f32 v69, v77, 0xba000000, v29
	v_fmamk_f32 v71, v77, 0xba000000, v28
	v_mov_b32_e32 v28, v30
	v_mov_b32_e32 v29, v26
	v_pk_mul_f32 v[32:33], v[32:33], v[32:33]
	v_mov_b32_e32 v68, v79
	v_pk_fma_f32 v[28:29], v[28:29], v[28:29], v[32:33]
	v_mov_b32_e32 v70, v78
	v_pk_mul_f32 v[32:33], v[68:69], v[68:69]
	v_fmamk_f32 v67, v77, 0xba000000, v21
	v_pk_fma_f32 v[32:33], v[70:71], v[70:71], v[32:33]
	v_fmamk_f32 v66, v77, 0xba000000, v20
	v_fmamk_f32 v19, v77, 0xba000000, v19
	v_fmac_f32_e32 v18, 0xba000000, v77
	v_pk_add_f32 v[28:29], v[28:29], v[32:33]
	v_pk_mul_f32 v[20:21], v[66:67], v[66:67]
	v_pk_mul_f32 v[32:33], v[18:19], v[18:19]
	v_fmac_f32_e32 v22, 0xba000000, v77
	v_pk_mov_b32 v[62:63], v[32:33], v[20:21] op_sel:[1,0]
	v_mov_b32_e32 v33, v21
	v_fmamk_f32 v64, v77, 0xba000000, v24
	v_fmamk_f32 v23, v77, 0xba000000, v23
	v_mul_f32_e32 v0, v22, v22
	v_pk_add_f32 v[20:21], v[62:63], v[32:33]
	v_fmamk_f32 v65, v77, 0xba000000, v25
	v_pk_fma_f32 v[24:25], v[22:23], v[22:23], v[0:1] op_sel_hi:[1,1,0]
	v_mul_f32_e32 v0, v64, v64
	v_pk_add_f32 v[28:29], v[28:29], v[28:29] op_sel_hi:[0,1]
	v_pk_add_f32 v[20:21], v[20:21], v[20:21] op_sel_hi:[0,1]
	v_pk_fma_f32 v[32:33], v[64:65], v[64:65], v[0:1] op_sel_hi:[1,1,0]
	v_fmamk_f32 v63, v77, 0xba000000, v13
	v_fmamk_f32 v62, v77, 0xba000000, v12
	v_fmamk_f32 v11, v77, 0xba000000, v11
	v_fmac_f32_e32 v10, 0xba000000, v77
	v_mul_f32_e32 v24, v10, v10
	v_mul_f32_e32 v32, v11, v11
	v_mul_f32_e32 v20, v62, v62
	v_mul_f32_e32 v28, v63, v63
	v_pk_add_f32 v[12:13], v[24:25], v[32:33]
	v_pk_add_f32 v[20:21], v[20:21], v[28:29]
	v_fmamk_f32 v33, v77, 0xba000000, v17
	v_pk_add_f32 v[12:13], v[12:13], v[20:21]
	v_fmamk_f32 v32, v77, 0xba000000, v16
	v_fmamk_f32 v15, v77, 0xba000000, v15
	v_fmac_f32_e32 v14, 0xba000000, v77
	v_pk_add_f32 v[20:21], v[12:13], v[12:13] op_sel_hi:[0,1]
	v_pk_mul_f32 v[12:13], v[32:33], v[32:33]
	v_pk_mul_f32 v[16:17], v[14:15], v[14:15]
	v_fmac_f32_e32 v6, 0xba000000, v77
	v_pk_mov_b32 v[24:25], v[16:17], v[12:13] op_sel:[1,0]
	v_mov_b32_e32 v17, v13
	v_pk_add_f32 v[12:13], v[24:25], v[16:17]
	v_fmamk_f32 v24, v77, 0xba000000, v8
	v_fmamk_f32 v7, v77, 0xba000000, v7
	v_mul_f32_e32 v0, v6, v6
	v_fmamk_f32 v25, v77, 0xba000000, v9
	v_pk_fma_f32 v[8:9], v[6:7], v[6:7], v[0:1] op_sel_hi:[1,1,0]
	v_mul_f32_e32 v0, v24, v24
	v_pk_add_f32 v[16:17], v[12:13], v[12:13] op_sel_hi:[0,1]
	v_pk_fma_f32 v[28:29], v[24:25], v[24:25], v[0:1] op_sel_hi:[1,1,0]
	v_fmamk_f32 v13, v77, 0xba000000, v5
	v_fmamk_f32 v12, v77, 0xba000000, v4
	v_fmamk_f32 v3, v77, 0xba000000, v3
	v_fmac_f32_e32 v2, 0xba000000, v77
	v_mul_f32_e32 v8, v2, v2
	v_mul_f32_e32 v28, v3, v3
	v_mul_f32_e32 v16, v12, v12
	v_mul_f32_e32 v20, v13, v13
	v_pk_add_f32 v[4:5], v[8:9], v[28:29]
	v_pk_add_f32 v[8:9], v[16:17], v[20:21]
	s_nop 0
	v_pk_add_f32 v[4:5], v[4:5], v[8:9]
	s_nop 0
	v_add_f32_e32 v0, v4, v5
	s_nop 1
	v_add_f32_dpp v0, v0, v0 quad_perm:[1,0,3,2] row_mask:0xf bank_mask:0xf
	s_nop 1
	v_add_f32_dpp v0, v0, v0 quad_perm:[2,3,0,1] row_mask:0xf bank_mask:0xf
	s_nop 1
	v_add_f32_dpp v0, v0, v0 row_half_mirror row_mask:0xf bank_mask:0xf
	s_nop 1
	v_add_f32_dpp v0, v0, v0 row_mirror row_mask:0xf bank_mask:0xf
	v_mov_b32_e32 v4, v0
	s_nop 1
	v_permlane16_swap_b32_e32 v0, v4
	v_add_f32_e32 v0, v0, v4
	v_mov_b32_e32 v4, v0
	s_nop 1
	v_permlane32_swap_b32_e32 v0, v4
	v_add_f32_e32 v0, v0, v4
	v_fmamk_f32 v0, v0, 0x3a000000, v169
	v_cmp_gt_f32_e32 vcc, s56, v0
	v_mul_f32_e32 v4, 0x4b800000, v0
	s_nop 0
	v_cndmask_b32_e32 v0, v0, v4, vcc
	v_rsq_f32_e32 v0, v0
	s_nop 0
	v_mul_f32_e32 v4, 0x45800000, v0
	v_cndmask_b32_e32 v20, v0, v4, vcc
	v_mov_b32_e32 v21, v20
	v_pk_mul_f32 v[4:5], v[30:31], v[20:21] op_sel_hi:[1,0]
	v_pk_mul_f32 v[8:9], v[78:79], v[20:21] op_sel_hi:[1,0]
	s_nop 1
	v_mov_b64_e32 v[28:29], v[86:87]
	v_mov_b64_e32 v[30:31], v[88:89]
	s_nop 1
	v_mov_b64_e32 v[78:79], v[118:119]
	v_mov_b64_e32 v[80:81], v[120:121]
	s_and_b64 vcc, exec, s[30:31]
	v_pk_fma_f32 v[30:31], v[30:31], v[8:9], v[80:81]
	v_pk_fma_f32 v[28:29], v[28:29], v[4:5], v[78:79]
	v_pk_mul_f32 v[4:5], v[26:27], v[20:21]
	global_store_dwordx4 v[60:61], v[28:31], off
	s_cbranch_vccz .LBB0_902
	s_nop 1
	v_mov_b64_e32 v[78:79], v[90:91]
	v_mov_b64_e32 v[80:81], v[92:93]
	s_nop 1
	v_mov_b64_e32 v[82:83], v[122:123]
	v_mov_b64_e32 v[84:85], v[124:125]
	v_mov_b32_e32 v8, v20
	v_mov_b32_e32 v9, v20
	v_mov_b32_e32 v68, v71
	v_pk_mul_f32 v[8:9], v[68:69], v[8:9]
	s_mov_b64 s[24:25], 0
	v_pk_fma_f32 v[80:81], v[8:9], v[80:81], v[84:85]
	v_pk_fma_f32 v[78:79], v[4:5], v[78:79], v[82:83]
	global_store_dwordx4 v[60:61], v[78:81], off offset:1024
